# attention softmax scale: 12 in-place v_fmamk_f32 pairs packed into v_pk_fma_f32 (scalar constant in SGPR)
# baseline (speedup 1.0000x reference)
; #define SBAR() __builtin_amdgcn_sched_barrier(0)
; #define SWRITE(b) SWRITE2(b, b)
; #define SWAIT() asm volatile("s_waitcnt vmcnt(0)" ::: "memory")
; template <int DK, int DV, int LDQ, int LDK, int LDV, int LDO, typename TOut, bool PIPE, bool QL, bool VS>
; __device__ __forceinline__ void attn_body16(const bf16_t* Qb, const bf16_t* Kh, const bf16_t* Vh, TOut* Ob, int seq, char* lds) {
;     ...
;     for (int ks = 0; ks < DK / 32; ++ks) { const bf16x8 qv = *reinterpret_cast<const bf16x8*>(Qb + (long)(wid * QBLK + qt * 16 + c) * LDQ + ks * 32 + g * 8);
;       if constexpr (QL) { *reinterpret_cast<bf16x8*>(Q_lds + (qt * 16 + c) * (DK * 2) + (((ks * 32 + g * 8) * 2) ^ ((c & 7) << 4))) = qv; if (qt == 0 && ks == 0) qr[0][0] = qv; } else qr[qt][ks] = qv; }
;     ...
;   const int vb0 = (int)(uintptr_t)V_lds + (4 * g + (c >> 2)) * VRSB + (c & 3) * 8;
;   struct { bf16x8 vs[VP], ks[PIPE ? KP : 1]; } sr_;
;   const int widu = __builtin_amdgcn_readfirstlane(wid);
;     ...
;   bf16x8 pa[2][2]; const int NT = seq / KVBLK;
;   if constexpr (PIPE) {
;     f32x4 sA[4][2], sB[4][2]; float alA[2], alB[2];
;     SLOAD(0); asm volatile("s_waitcnt vmcnt(0)" ::: "memory"); SWRITE(0); __syncthreads();
;     QKT(sA, K_lds); partialSM16(sA, m_reg, alA, C, THR_S);
;     SLOAD(KVBLK);
;     SWAIT(); SWRITE(1); __syncthreads();
;     for (int j = 1; j + 1 < NT; j += 2) {
;       SLOAD((j + 1) * KVBLK); SBAR(); QKT(sB, K_lds + SHM_K); SBAR();
;       finishSM16(sA, alA, lp, pa); SBAR();
;       pv16<NVT, VRSB>(o, vb0, pa); partialSM16(sB, m_reg, alB, C, THR_S);
;       __syncthreads(); SWAIT(); SWRITE(0);
;       RESC(alB); __syncthreads();
;       SLOAD((j + 2) * KVBLK); SBAR(); QKT(sA, K_lds); SBAR();
;       finishSM16(sB, alB, lp, pa); SBAR();
;       pv16<NVT, VRSB>(o, vb0 + (int)SHM_V, pa); partialSM16(sA, m_reg, alA, C, THR_S);
;       __syncthreads(); SWAIT(); SWRITE(1);
;       RESC(alA); __syncthreads();
;     }
;     SBAR(); QKT(sB, K_lds + SHM_K); SBAR();
;     finishSM16(sA, alA, lp, pa); SBAR();
;     pv16<NVT, VRSB>(o, vb0, pa); partialSM16(sB, m_reg, alB, C, THR_S);
;     __syncthreads(); RESC(alB);
;     finishSM16(sB, alB, lp, pa); SBAR();
;     pv16<NVT, VRSB>(o, vb0 + (int)SHM_V, pa);
;   } else {
;     f32x4 s[4][2]; float al[2];
;     VLOAD(0); KDMA(0, 0); asm volatile("s_waitcnt vmcnt(0)" ::: "memory"); VWRITE(0); __syncthreads();
.LBB0_673:
	s_andn2_b64 vcc, exec, s[6:7]
	s_cbranch_vccnz .LBB0_668
	s_ashr_i32 s27, s26, 3
	s_and_b32 s28, s26, 7
	s_mul_i32 s7, s27, 0x1100
	s_mul_hi_i32 s6, s27, 0x1100
	s_add_u32 s12, s7, s4
	s_addc_u32 s13, s6, s5
	s_mul_i32 s4, s13, 0xc00
	s_mul_hi_u32 s5, s12, 0xc00
	s_add_i32 s5, s5, s4
	s_mul_i32 s4, s12, 0xc00
	s_add_u32 s4, s1, s4
	s_addc_u32 s5, s16, s5
	s_mul_i32 s33, s28, 0x180
	s_add_u32 s6, s4, s33
	s_addc_u32 s7, s5, 0
	s_mul_i32 s37, s27, 0xcc0000
	v_mov_b32_e32 v22, v0
	s_mul_hi_i32 s36, s27, 0xcc0000
	s_add_u32 s4, s17, s37
	s_addc_u32 s5, s20, s36
	v_add_u32_e32 v17, 0x200, v22
	v_ashrrev_i32_e32 v2, 31, v22
	v_ashrrev_i32_e32 v6, 31, v17
	s_add_u32 s4, s4, s33
	v_ashrrev_i32_e32 v155, 6, v22
	v_bfe_u32 v170, v22, 4, 2
	v_lshrrev_b32_e32 v2, 28, v2
	v_lshrrev_b32_e32 v6, 28, v6
	s_addc_u32 s5, s5, 0
	s_mul_i32 s39, s27, 0x880000
	v_and_b32_e32 v171, 15, v22
	v_lshlrev_b32_e32 v154, 5, v155
	v_lshlrev_b32_e32 v10, 4, v170
	v_mov_b32_e32 v11, v179
	v_add_u32_e32 v2, v22, v2
	v_add_u32_e32 v6, v17, v6
	s_mul_hi_i32 s38, s27, 0x880000
	s_add_u32 s27, s21, s39
	v_or_b32_e32 v15, v154, v171
	v_lshl_add_u64 v[12:13], s[6:7], 0, v[10:11]
	v_ashrrev_i32_e32 v11, 4, v2
	v_and_b32_e32 v2, 0xffffff0, v2
	v_ashrrev_i32_e32 v23, 4, v6
	v_and_b32_e32 v6, 0xffffff0, v6
	s_addc_u32 s29, s22, s38
	s_lshl_b32 s26, s28, 7
	s_lshl_b32 s46, s28, 8
	v_sub_u32_e32 v2, v22, v2
	v_sub_u32_e32 v6, v17, v6
	v_mad_i64_i32 v[18:19], s[6:7], v15, s47, v[12:13]
	v_or_b32_e32 v15, 16, v15
	s_add_u32 s28, s27, s46
	v_lshlrev_b32_e32 v177, 4, v2
	v_lshlrev_b32_e32 v186, 4, v6
	v_mad_i64_i32 v[12:13], s[6:7], v15, s47, v[12:13]
	s_addc_u32 s29, s29, 0
	v_lshl_add_u32 v14, v11, 11, v177
	v_lshl_add_u32 v16, v23, 11, v186
	v_readfirstlane_b32 s6, v155
	s_add_i32 s50, 0, 0x15000
	global_load_dwordx4 v[2:5], v14, s[28:29]
	global_load_dwordx4 v[6:9], v16, s[28:29]
	s_lshl_b32 s28, s6, 10
	s_add_i32 s27, 0, 0x9000
	s_cmp_lg_u32 s27, -1
	s_cselect_b32 s6, s27, 0
	s_add_i32 s28, s28, s6
	s_mov_b32 s6, 0x2aaaaaab
	global_load_dwordx4 v[102:105], v[18:19], off
	global_load_dwordx4 v[94:97], v[18:19], off offset:64
	global_load_dwordx4 v[86:89], v[18:19], off offset:128
	global_load_dwordx4 v[78:81], v[18:19], off offset:192
	global_load_dwordx4 v[70:73], v[18:19], off offset:256
	global_load_dwordx4 v[66:69], v[18:19], off offset:320
	global_load_dwordx4 v[110:113], v[12:13], off
	global_load_dwordx4 v[106:109], v[12:13], off offset:64
	global_load_dwordx4 v[98:101], v[12:13], off offset:128
	global_load_dwordx4 v[90:93], v[12:13], off offset:192
	global_load_dwordx4 v[82:85], v[12:13], off offset:256
	global_load_dwordx4 v[74:77], v[12:13], off offset:320
	v_mul_hi_i32 v12, v22, s6
	v_lshrrev_b32_e32 v13, 31, v12
	v_ashrrev_i32_e32 v12, 2, v12
	v_add_u32_e32 v12, v12, v13
	v_mul_lo_u32 v13, v12, 24
	v_sub_u32_e32 v13, v22, v13
	v_bitop3_b32 v13, v12, v13, 7 bitop3:0x6c
	v_mul_lo_u32 v12, v12, s47
	v_lshl_add_u32 v12, v13, 4, v12
	v_mul_hi_i32 v13, v17, s6
	v_lshrrev_b32_e32 v15, 31, v13
	v_ashrrev_i32_e32 v13, 2, v13
	v_add_u32_e32 v13, v13, v15
	v_mul_lo_u32 v15, v13, 24
	v_sub_u32_e32 v15, v17, v15
	v_bitop3_b32 v15, v13, v15, 7 bitop3:0x6c
	v_mul_lo_u32 v13, v13, s47
	v_lshl_add_u32 v18, v15, 4, v13
	v_add_u32_e32 v13, 0x400, v22
	v_mul_hi_i32 v15, v13, s6
	v_lshrrev_b32_e32 v17, 31, v15
	v_ashrrev_i32_e32 v15, 2, v15
	v_add_u32_e32 v15, v15, v17
	v_mul_lo_u32 v17, v15, 24
	s_mov_b32 m0, s28
	v_sub_u32_e32 v13, v13, v17
	global_load_lds_dwordx4 v12, s[4:5]
	s_add_i32 m0, s28, 0x2000
	v_bitop3_b32 v13, v15, v13, 7 bitop3:0x6c
	v_mul_lo_u32 v15, v15, s47
	global_load_lds_dwordx4 v18, s[4:5]
	v_lshl_add_u32 v20, v13, 4, v15
	s_add_i32 m0, s28, 0x4000
	s_cmp_lg_u32 0, -1
	global_load_lds_dwordx4 v20, s[4:5]
	s_movk_i32 s4, 0x120
	v_mul_lo_u32 v187, v11, s4
	v_add3_u32 v11, 0, v187, v177
	v_mul_lo_u32 v188, v23, s4
	s_waitcnt vmcnt(0)
	s_cselect_b32 s6, 0, 0
	s_add_i32 s30, s30, 1
	v_and_b32_e32 v13, 0x3fffffc0, v22
	v_lshl_add_u32 v24, v13, 2, s50
	v_mov_b32_e32 v13, v179
	v_mov_b32_e32 v19, v179
	v_mov_b32_e32 v21, v179
	v_lshlrev_b32_e32 v178, 4, v171
	s_movk_i32 s4, 0x70
	v_bitop3_b32 v190, v10, v178, s4 bitop3:0x78
	s_movk_i32 s4, 0xc0
	v_mov_b32_e32 v15, v179
	v_mov_b32_e32 v17, v179
	v_mov_b32_e32 v58, v179
	v_mov_b32_e32 v59, v179
	v_mov_b32_e32 v60, v179
	v_mov_b32_e32 v61, v179
	v_lshl_add_u32 v173, v171, 2, v24
	v_add_u32_e32 v172, v24, v10
	v_mov_b32_e32 v156, 0
	v_mov_b64_e32 v[50:51], v[58:59]
	v_mov_b64_e32 v[42:43], v[58:59]
	v_mov_b64_e32 v[34:35], v[58:59]
	v_mov_b64_e32 v[26:27], v[58:59]
	v_mov_b64_e32 v[64:65], v[60:61]
	v_mov_b64_e32 v[54:55], v[58:59]
	v_mov_b64_e32 v[46:47], v[58:59]
	s_waitcnt vmcnt(0)
	ds_write_b128 v11, v[2:5]
	v_add3_u32 v2, 0, v188, v186
	ds_write_b128 v2, v[6:9]
	v_bfe_u32 v2, v22, 2, 2
	v_lshl_or_b32 v2, v170, 2, v2
	v_lshlrev_b32_e32 v3, 3, v22
	v_mul_u32_u24_e32 v2, 0x120, v2
	v_and_b32_e32 v3, 24, v3
	v_add3_u32 v174, v3, s6, v2
	s_or_b32 s6, s37, s33
	s_add_u32 s6, s6, 0x325d0000
	s_addc_u32 s7, s36, 0
	v_and_b32_e32 v4, 0x70, v178
	v_lshl_add_u64 v[158:159], s[6:7], 0, v[12:13]
	v_lshl_add_u64 v[160:161], s[6:7], 0, v[18:19]
	v_lshl_add_u64 v[162:163], s[6:7], 0, v[20:21]
	s_or_b32 s6, s39, s46
	v_bitop3_b32 v193, v10, v4, s4 bitop3:0x36
	s_movk_i32 s4, 0x100
	s_add_u32 s6, s6, 0x358c0000
	v_bitop3_b32 v194, v10, v4, s4 bitop3:0x36
	s_movk_i32 s4, 0x140
	s_addc_u32 s7, s38, 0
	v_bitop3_b32 v191, v10, v4, 64 bitop3:0x36
	v_bitop3_b32 v192, v10, v4, s14 bitop3:0x36
	v_bitop3_b32 v195, v10, v4, s4 bitop3:0x36
	v_lshl_add_u64 v[164:165], s[6:7], 0, v[14:15]
	v_lshl_add_u64 v[166:167], s[6:7], 0, v[16:17]
	v_mov_b64_e32 v[18:19], v[58:59]
	v_mov_b64_e32 v[10:11], v[58:59]
	v_mov_b64_e32 v[2:3], v[58:59]
	v_mov_b64_e32 v[38:39], v[58:59]
	v_mov_b64_e32 v[30:31], v[58:59]
	v_mov_b64_e32 v[22:23], v[58:59]
	v_mov_b64_e32 v[14:15], v[58:59]
	v_mov_b64_e32 v[6:7], v[58:59]
	s_mov_b32 s29, 0
	v_mul_u32_u24_e32 v189, 0x180, v171
	v_cmp_eq_u32_e64 s[4:5], 0, v170
	v_mov_b32_e32 v175, 0xf149f2ca
	v_mov_b64_e32 v[52:53], v[60:61]
	v_mov_b64_e32 v[44:45], v[60:61]
	v_mov_b64_e32 v[36:37], v[60:61]
	v_mov_b64_e32 v[28:29], v[60:61]
	v_mov_b64_e32 v[20:21], v[60:61]
	v_mov_b64_e32 v[12:13], v[60:61]
	v_mov_b64_e32 v[4:5], v[60:61]
	v_mov_b64_e32 v[62:63], v[58:59]
	v_mov_b64_e32 v[56:57], v[60:61]
	v_mov_b64_e32 v[48:49], v[60:61]
	v_mov_b64_e32 v[40:41], v[60:61]
	v_mov_b64_e32 v[32:33], v[60:61]
	v_mov_b64_e32 v[24:25], v[60:61]
	v_mov_b64_e32 v[16:17], v[60:61]
	v_mov_b64_e32 v[8:9], v[60:61]
	v_mov_b32_e32 v176, 0xf149f2ca
	v_mov_b32_e32 v157, v156
	s_waitcnt lgkmcnt(0)
	s_barrier
	s_mov_b64 s[52:53], s[8:9]
	s_mov_b64 s[54:55], s[8:9]
	s_mov_b32 s62, 0x3dd53b94
	s_branch .LBB0_677

; #define SBAR() __builtin_amdgcn_sched_barrier(0)
; #define RESC(a) do { if (__any((a) < 1.f)) { if (hi == 0) al_l[r32] = (a); asm volatile("s_waitcnt lgkmcnt(0)" ::: "memory"); \
;     _Pragma("unroll") for (int d = 0; d < 4; ++d) _Pragma("unroll") for (int r = 0; r < 16; ++r) o[d][r] *= al_l[crow(r, hi)]; } } while (0)
; template <int NVT, int VRSB, int KB, int DH, int VT> __device__ __forceinline__ void pvh_pro(int vb, s16x4 (&f)[DH + 1][2]) { if constexpr (VT < DH && VT < NVT) { pvh_ld<VT, KB, VRSB>(f[VT], vb); pvh_pro<NVT, VRSB, KB, DH, VT + 1>(vb, f); } }
; __device__ __forceinline__ void partialSM16(f32x4 (&s)[4][2], float (&m_reg)[2], float (&alpha)[2], const float C, const float thr_s) {
;     ...
;   for (int qt = 0; qt < 2; ++qt) { const float mnC = -mn[qt] * C;
; #pragma unroll
;     for (int kt = 0; kt < 4; ++kt)
; #pragma unroll
;       for (int r = 0; r < 4; ++r) s[kt][qt][r] = fmaf(s[kt][qt][r], C, mnC); }
; #pragma unroll
;   for (int qt = 0; qt < 2; ++qt)
; #pragma unroll
;     for (int kt = 0; kt < 2; ++kt)
; #pragma unroll
;       for (int r = 0; r < 4; ++r) s[kt][qt][r] = __builtin_amdgcn_exp2f(s[kt][qt][r]);
; template <int DK, int DV, int LDQ, int LDK, int LDV, int LDO, typename TOut, bool PIPE, bool QL, bool VS>
; __device__ __forceinline__ void attn_body16(const bf16_t* Qb, const bf16_t* Kh, const bf16_t* Vh, TOut* Ob, int seq, char* lds) {
;     ...
;       partialSM16(s, m_reg, al, C, THR_S);
;       RESC(al);
;       constexpr int DH = 3; s16x4 pvf[DH + 1][2]; const int vbt = vb0 + vsel * (int)SHM_V;
;       pvh_pro<NVT, VRSB, 0, DH, 0>(vbt, pvf); SBAR();
;       cvt_pa(s, pa, 0); SBAR();
;       pvh_step<NVT, VRSB, 0, DH, true, 0>(o, vbt, pa, pvf, s);
.LBB0_676:
	v_mul_f32_e32 v196, 0xbdd53b94, v176
	v_fmamk_f32 v197, v142, 0x3dd53b94, v196
	v_mul_f32_e32 v142, 0xbdd53b94, v175
	v_pk_fma_f32 v[122:123], v[122:123], s[62:63], v[142:143] op_sel_hi:[1,0,0]
	s_mulk_i32 s36, 0x4800
	v_fmamk_f32 v213, v151, 0x3dd53b94, v196
	v_pk_fma_f32 v[124:125], v[124:125], s[62:63], v[142:143] op_sel_hi:[1,0,0]
	v_fmamk_f32 v222, v149, 0x3dd53b94, v142
	v_exp_f32_e32 v149, v122
	v_exp_f32_e32 v151, v123
	v_add_u32_e32 v223, s36, v174
	ds_read_b64_tr_b16 v[122:123], v223 offset:0
	v_pk_fma_f32 v[126:127], v[126:127], s[62:63], v[196:197] op_sel_hi:[1,0,0]
	v_fmamk_f32 v217, v153, 0x3dd53b94, v196
	v_exp_f32_e32 v153, v124
	v_exp_f32_e32 v183, v125
	ds_read_b64_tr_b16 v[124:125], v223 offset:0x1200
	v_pk_fma_f32 v[128:129], v[128:129], s[62:63], v[196:197] op_sel_hi:[1,0,0]
	v_fmamk_f32 v212, v150, 0x3dd53b94, v196
	v_fmamk_f32 v221, v148, 0x3dd53b94, v142
	v_exp_f32_e32 v148, v126
	v_exp_f32_e32 v150, v127
	ds_read_b64_tr_b16 v[126:127], v223 offset:32
	v_fmamk_f32 v215, v152, 0x3dd53b94, v196
	v_pk_fma_f32 v[130:131], v[130:131], s[62:63], v[142:143] op_sel_hi:[1,0,0]
	v_exp_f32_e32 v152, v128
	v_exp_f32_e32 v182, v129
	ds_read_b64_tr_b16 v[128:129], v223 offset:0x1220
	v_pk_fma_f32 v[132:133], v[132:133], s[62:63], v[142:143] op_sel_hi:[1,0,0]
	v_exp_f32_e32 v185, v130
	v_exp_f32_e32 v199, v131
	ds_read_b64_tr_b16 v[130:131], v223 offset:64
	v_exp_f32_e32 v201, v132
	v_exp_f32_e32 v203, v133
	ds_read_b64_tr_b16 v[132:133], v223 offset:0x1240
	v_pk_fma_f32 v[134:135], v[134:135], s[62:63], v[196:197] op_sel_hi:[1,0,0]
	v_pk_fma_f32 v[136:137], v[136:137], s[62:63], v[196:197] op_sel_hi:[1,0,0]
	s_add_i32 s29, s29, 1
	v_fmamk_f32 v143, v143, 0x3dd53b94, v196
	v_fmamk_f32 v205, v144, 0x3dd53b94, v196
	v_fmamk_f32 v207, v145, 0x3dd53b94, v196
	v_fmamk_f32 v209, v138, 0x3dd53b94, v142
	v_fmamk_f32 v211, v139, 0x3dd53b94, v142
	v_fmamk_f32 v214, v140, 0x3dd53b94, v142
	v_fmamk_f32 v216, v141, 0x3dd53b94, v142
	v_fmamk_f32 v219, v146, 0x3dd53b94, v142
	v_fmamk_f32 v220, v147, 0x3dd53b94, v142
	v_exp_f32_e32 v184, v134
	v_exp_f32_e32 v198, v135
	v_exp_f32_e32 v200, v136
	v_exp_f32_e32 v202, v137
	v_cvt_pk_bf16_f32 v134, v148, v150
	v_cvt_pk_bf16_f32 v135, v152, v182
	v_cvt_pk_bf16_f32 v136, v184, v198
	v_cvt_pk_bf16_f32 v137, v200, v202
	v_cvt_pk_bf16_f32 v138, v149, v151
	v_cvt_pk_bf16_f32 v139, v153, v183
	v_cvt_pk_bf16_f32 v140, v185, v199
	v_cvt_pk_bf16_f32 v141, v201, v203
	ds_read_b64_tr_b16 v[144:145], v223 offset:0x60
	ds_read_b64_tr_b16 v[146:147], v223 offset:0x1260
	s_waitcnt lgkmcnt(6)
	v_mfma_f32_16x16x32_bf16 v[58:61], v[134:137], v[122:125], v[58:61]
	v_exp_f32_e32 v204, v197
	v_exp_f32_e32 v206, v143
	v_mfma_f32_16x16x32_bf16 v[62:65], v[138:141], v[122:125], v[62:65]
	ds_read_b64_tr_b16 v[122:123], v223 offset:0x80
	ds_read_b64_tr_b16 v[124:125], v223 offset:0x1280
	s_waitcnt lgkmcnt(6)
	v_mfma_f32_16x16x32_bf16 v[50:53], v[134:137], v[126:129], v[50:53]
	v_exp_f32_e32 v208, v205
	v_exp_f32_e32 v210, v207
	v_mfma_f32_16x16x32_bf16 v[54:57], v[138:141], v[126:129], v[54:57]
	ds_read_b64_tr_b16 v[126:127], v223 offset:0xa0
	ds_read_b64_tr_b16 v[128:129], v223 offset:0x12a0
	s_waitcnt lgkmcnt(6)
	v_mfma_f32_16x16x32_bf16 v[42:45], v[134:137], v[130:133], v[42:45]
	v_exp_f32_e32 v205, v209
	v_exp_f32_e32 v207, v211
	v_mfma_f32_16x16x32_bf16 v[46:49], v[138:141], v[130:133], v[46:49]
	ds_read_b64_tr_b16 v[130:131], v223 offset:0xc0
	ds_read_b64_tr_b16 v[132:133], v223 offset:0x12c0
	s_waitcnt lgkmcnt(6)
	v_mfma_f32_16x16x32_bf16 v[34:37], v[134:137], v[144:147], v[34:37]
	v_exp_f32_e32 v209, v214
	v_exp_f32_e32 v211, v216
	v_mfma_f32_16x16x32_bf16 v[38:41], v[138:141], v[144:147], v[38:41]
	ds_read_b64_tr_b16 v[144:145], v223 offset:0xe0
	ds_read_b64_tr_b16 v[146:147], v223 offset:0x12e0
	s_waitcnt lgkmcnt(6)
	v_mfma_f32_16x16x32_bf16 v[26:29], v[134:137], v[122:125], v[26:29]
	v_exp_f32_e32 v212, v212
	v_exp_f32_e32 v214, v213
	v_mfma_f32_16x16x32_bf16 v[30:33], v[138:141], v[122:125], v[30:33]
	s_waitcnt lgkmcnt(4)
	v_mfma_f32_16x16x32_bf16 v[18:21], v[134:137], v[126:129], v[18:21]
	v_exp_f32_e32 v216, v215
	v_exp_f32_e32 v218, v217
	v_mfma_f32_16x16x32_bf16 v[22:25], v[138:141], v[126:129], v[22:25]
	s_waitcnt lgkmcnt(2)
; #define SBAR() __builtin_amdgcn_sched_barrier(0)
; template <int NVT, int VRSB, int KB, int DH, int VT> __device__ __forceinline__ void pvh_pro(int vb, s16x4 (&f)[DH + 1][2]) { if constexpr (VT < DH && VT < NVT) { pvh_ld<VT, KB, VRSB>(f[VT], vb); pvh_pro<NVT, VRSB, KB, DH, VT + 1>(vb, f); } }
; #define VWRITE(bv) do { _Pragma("unroll") for (int _q = 0; _q < VP; ++_q) *(bf16x8*)(V_lds + (bv) * SHM_V + VROW(_q) * VRSB + VC8(_q) * 16) = sr_.vs[_q]; } while (0)
; template <int DK, int DV, int LDQ, int LDK, int LDV, int LDO, typename TOut, bool PIPE, bool QL, bool VS>
; __device__ __forceinline__ void attn_body16(const bf16_t* Qb, const bf16_t* Kh, const bf16_t* Vh, TOut* Ob, int seq, char* lds) {
;     ...
;       pvh_step<NVT, VRSB, 0, DH, true, 0>(o, vbt, pa, pvf, s);
;       pvh_pro<NVT, VRSB, 1, DH, 0>(vbt, pvf); SBAR();
; #pragma unroll
;       for (int qt = 0; qt < 2; ++qt) { float ps = 0.f;
; #pragma unroll
;         for (int kt = 0; kt < 4; ++kt) ps += (s[kt][qt][0] + s[kt][qt][1]) + (s[kt][qt][2] + s[kt][qt][3]);
;         lp[qt] = lp[qt] * al[qt] + ps; }
;       cvt_pa(s, pa, 1); SBAR();
;       pvh_step<NVT, VRSB, 1, DH, false, 0>(o, vbt, pa, pvf, s);
;       if constexpr (VS) {
;         asm volatile("s_waitcnt vmcnt(0)" ::: "memory");
;         __syncthreads();
;         if (j + 1 < NT) VWRITE(0);
;       } else if (j + 1 < NT) { asm volatile("s_waitcnt vmcnt(0)" ::: "memory"); VWRITE(bsel ^ 1); }
;       __syncthreads();
	v_mfma_f32_16x16x32_bf16 v[10:13], v[134:137], v[130:133], v[10:13]
	v_exp_f32_e32 v213, v219
	v_exp_f32_e32 v215, v220
	v_mfma_f32_16x16x32_bf16 v[14:17], v[138:141], v[130:133], v[14:17]
	s_waitcnt lgkmcnt(0)
	v_mfma_f32_16x16x32_bf16 v[2:5], v[134:137], v[144:147], v[2:5]
	v_exp_f32_e32 v217, v221
	v_exp_f32_e32 v219, v222
	v_mfma_f32_16x16x32_bf16 v[6:9], v[138:141], v[144:147], v[6:9]
	ds_read_b64_tr_b16 v[122:123], v223 offset:0x2400
	ds_read_b64_tr_b16 v[124:125], v223 offset:0x3600
	ds_read_b64_tr_b16 v[126:127], v223 offset:0x2420
	ds_read_b64_tr_b16 v[128:129], v223 offset:0x3620
	ds_read_b64_tr_b16 v[130:131], v223 offset:0x2440
	ds_read_b64_tr_b16 v[132:133], v223 offset:0x3640
	v_add_f32_e64 v134, v148, v150
	v_add_f32_e64 v135, v149, v151
	v_pk_add_f32 v[136:137], v[152:153], v[182:183]
	v_pk_add_f32 v[138:139], v[184:185], v[198:199]
	v_pk_add_f32 v[140:141], v[200:201], v[202:203]
	v_pk_add_f32 v[134:135], v[134:135], v[136:137]
	v_pk_add_f32 v[136:137], v[138:139], v[140:141]
	v_pk_add_f32 v[134:135], v[134:135], 0 op_sel_hi:[1,0]
	v_pk_add_f32 v[138:139], v[208:209], v[210:211]
	v_pk_add_f32 v[134:135], v[136:137], v[134:135]
	v_pk_add_f32 v[136:137], v[204:205], v[206:207]
	v_cvt_pk_bf16_f32 v140, v213, v215
	v_pk_add_f32 v[136:137], v[136:137], v[138:139]
	v_pk_add_f32 v[138:139], v[216:217], v[218:219]
	v_pk_add_f32 v[134:135], v[136:137], v[134:135]
	v_pk_add_f32 v[136:137], v[212:213], v[214:215]
	v_cvt_pk_bf16_f32 v141, v217, v219
	v_pk_add_f32 v[136:137], v[136:137], v[138:139]
	v_cvt_pk_bf16_f32 v138, v205, v207
	v_pk_add_f32 v[134:135], v[136:137], v[134:135]
	v_cvt_pk_bf16_f32 v136, v212, v214
	v_pk_fma_f32 v[156:157], v[156:157], v[168:169], v[134:135]
	v_cvt_pk_bf16_f32 v134, v204, v206
	v_cvt_pk_bf16_f32 v135, v208, v210
	v_cvt_pk_bf16_f32 v137, v216, v218
	v_cvt_pk_bf16_f32 v139, v209, v211
	ds_read_b64_tr_b16 v[144:145], v223 offset:0x2460
	ds_read_b64_tr_b16 v[146:147], v223 offset:0x3660
	s_waitcnt lgkmcnt(6)
	s_nop 0
	v_mfma_f32_16x16x32_bf16 v[58:61], v[134:137], v[122:125], v[58:61]
	v_mfma_f32_16x16x32_bf16 v[62:65], v[138:141], v[122:125], v[62:65]
	ds_read_b64_tr_b16 v[122:123], v223 offset:0x2480
	ds_read_b64_tr_b16 v[124:125], v223 offset:0x3680
	s_waitcnt lgkmcnt(6)
	v_mfma_f32_16x16x32_bf16 v[50:53], v[134:137], v[126:129], v[50:53]
	v_mfma_f32_16x16x32_bf16 v[54:57], v[138:141], v[126:129], v[54:57]
	ds_read_b64_tr_b16 v[126:127], v223 offset:0x24a0
	ds_read_b64_tr_b16 v[128:129], v223 offset:0x36a0
	s_waitcnt lgkmcnt(6)
	v_mfma_f32_16x16x32_bf16 v[42:45], v[134:137], v[130:133], v[42:45]
	v_mfma_f32_16x16x32_bf16 v[46:49], v[138:141], v[130:133], v[46:49]
	ds_read_b64_tr_b16 v[130:131], v223 offset:0x24c0
	ds_read_b64_tr_b16 v[132:133], v223 offset:0x36c0
	s_waitcnt lgkmcnt(6)
	v_mfma_f32_16x16x32_bf16 v[34:37], v[134:137], v[144:147], v[34:37]
	v_mfma_f32_16x16x32_bf16 v[38:41], v[138:141], v[144:147], v[38:41]
	ds_read_b64_tr_b16 v[144:145], v223 offset:0x24e0
	ds_read_b64_tr_b16 v[146:147], v223 offset:0x36e0
	s_waitcnt lgkmcnt(6)
	v_mfma_f32_16x16x32_bf16 v[26:29], v[134:137], v[122:125], v[26:29]
	v_mfma_f32_16x16x32_bf16 v[30:33], v[138:141], v[122:125], v[30:33]
	s_waitcnt lgkmcnt(4)
	v_mfma_f32_16x16x32_bf16 v[18:21], v[134:137], v[126:129], v[18:21]
	v_mfma_f32_16x16x32_bf16 v[22:25], v[138:141], v[126:129], v[22:25]
	s_waitcnt lgkmcnt(2)
	v_mfma_f32_16x16x32_bf16 v[10:13], v[134:137], v[130:133], v[10:13]
	v_mfma_f32_16x16x32_bf16 v[14:17], v[138:141], v[130:133], v[14:17]
	s_waitcnt lgkmcnt(0)
	v_mfma_f32_16x16x32_bf16 v[2:5], v[134:137], v[144:147], v[2:5]
	v_mfma_f32_16x16x32_bf16 v[6:9], v[138:141], v[144:147], v[6:9]
	s_mulk_i32 s33, 0x4800
	s_waitcnt vmcnt(0)
	s_add_i32 s6, s33, 0
	v_add3_u32 v122, s6, v187, v177
	s_waitcnt vmcnt(0)
	ds_write_b128 v122, v[118:121]
	v_add3_u32 v118, s6, v188, v186
	s_add_u32 s52, s52, s80
	s_addc_u32 s53, s53, s81
	s_add_u32 s54, s54, s96
	s_addc_u32 s55, s55, s97
	s_cmp_eq_u32 s30, s29
	ds_write_b128 v118, v[114:117]
	s_waitcnt lgkmcnt(0)
	s_barrier
	s_cbranch_scc1 .LBB0_683

; #define SBAR() __builtin_amdgcn_sched_barrier(0)
; #define SWRITE(b) SWRITE2(b, b)
; #define SWAIT() asm volatile("s_waitcnt vmcnt(0)" ::: "memory")
; template <int DK, int DV, int LDQ, int LDK, int LDV, int LDO, typename TOut, bool PIPE, bool QL, bool VS>
; __device__ __forceinline__ void attn_body16(const bf16_t* Qb, const bf16_t* Kh, const bf16_t* Vh, TOut* Ob, int seq, char* lds) {
;     ...
;     for (int ks = 0; ks < DK / 32; ++ks) { const bf16x8 qv = *reinterpret_cast<const bf16x8*>(Qb + (long)(wid * QBLK + qt * 16 + c) * LDQ + ks * 32 + g * 8);
;       if constexpr (QL) { *reinterpret_cast<bf16x8*>(Q_lds + (qt * 16 + c) * (DK * 2) + (((ks * 32 + g * 8) * 2) ^ ((c & 7) << 4))) = qv; if (qt == 0 && ks == 0) qr[0][0] = qv; } else qr[qt][ks] = qv; }
;     ...
;   const int vb0 = (int)(uintptr_t)V_lds + (4 * g + (c >> 2)) * VRSB + (c & 3) * 8;
;   struct { bf16x8 vs[VP], ks[PIPE ? KP : 1]; } sr_;
;   const int widu = __builtin_amdgcn_readfirstlane(wid);
;     ...
;   bf16x8 pa[2][2]; const int NT = seq / KVBLK;
;   if constexpr (PIPE) {
;     f32x4 sA[4][2], sB[4][2]; float alA[2], alB[2];
;     SLOAD(0); asm volatile("s_waitcnt vmcnt(0)" ::: "memory"); SWRITE(0); __syncthreads();
;     QKT(sA, K_lds); partialSM16(sA, m_reg, alA, C, THR_S);
;     SLOAD(KVBLK);
;     SWAIT(); SWRITE(1); __syncthreads();
;     for (int j = 1; j + 1 < NT; j += 2) {
;       SLOAD((j + 1) * KVBLK); SBAR(); QKT(sB, K_lds + SHM_K); SBAR();
;       finishSM16(sA, alA, lp, pa); SBAR();
;       pv16<NVT, VRSB>(o, vb0, pa); partialSM16(sB, m_reg, alB, C, THR_S);
;       __syncthreads(); SWAIT(); SWRITE(0);
;       RESC(alB); __syncthreads();
;       SLOAD((j + 2) * KVBLK); SBAR(); QKT(sA, K_lds); SBAR();
;       finishSM16(sB, alB, lp, pa); SBAR();
;       pv16<NVT, VRSB>(o, vb0 + (int)SHM_V, pa); partialSM16(sA, m_reg, alA, C, THR_S);
;       __syncthreads(); SWAIT(); SWRITE(1);
;       RESC(alA); __syncthreads();
;     }
;     SBAR(); QKT(sB, K_lds + SHM_K); SBAR();
;     finishSM16(sA, alA, lp, pa); SBAR();
;     pv16<NVT, VRSB>(o, vb0, pa); partialSM16(sB, m_reg, alB, C, THR_S);
;     __syncthreads(); RESC(alB);
;     finishSM16(sB, alB, lp, pa); SBAR();
;     pv16<NVT, VRSB>(o, vb0 + (int)SHM_V, pa);
;   } else {
;     f32x4 s[4][2]; float al[2];
;     VLOAD(0); KDMA(0, 0); asm volatile("s_waitcnt vmcnt(0)" ::: "memory"); VWRITE(0); __syncthreads();
.LBB0_698:
	s_ashr_i32 s11, s10, 3
	s_and_b32 s26, s10, 1
	s_mul_i32 s7, s11, 0x1100
	s_mul_hi_i32 s6, s11, 0x1100
	s_add_u32 s8, s7, s4
	s_addc_u32 s9, s6, s5
	s_mul_i32 s4, s9, 0x3080
	s_mul_hi_u32 s5, s8, 0x3080
	s_add_i32 s5, s5, s4
	s_mul_i32 s4, s8, 0x3080
	s_add_u32 s4, s1, s4
	s_addc_u32 s5, s16, s5
	s_lshl_b32 s6, s10, 7
	s_and_b32 s27, s6, 0x300
	s_lshl_b32 s12, s27, 1
	s_add_u32 s4, s4, s12
	s_addc_u32 s5, s5, 0
	s_lshl_b32 s6, s26, 8
	v_mov_b32_e32 v37, v0
	s_add_u32 s4, s4, s6
	s_addc_u32 s5, s5, 0
	v_bfe_u32 v252, v37, 4, 2
	v_ashrrev_i32_e32 v187, 6, v37
	v_lshlrev_b32_e32 v34, 4, v252
	v_mov_b32_e32 v35, v179
	v_and_b32_e32 v253, 15, v37
	v_lshlrev_b32_e32 v186, 5, v187
	v_lshl_add_u64 v[2:3], s[4:5], 0, v[34:35]
	s_mov_b64 s[4:5], 0x1800
	v_or_b32_e32 v20, v186, v253
	v_lshl_add_u64 v[18:19], v[2:3], 0, s[4:5]
	v_mad_i64_i32 v[14:15], s[4:5], v20, s84, v[18:19]
	global_load_dwordx4 v[2:5], v[14:15], off
	global_load_dwordx4 v[6:9], v[14:15], off offset:64
	v_or_b32_e32 v20, 16, v20
	v_mad_i64_i32 v[30:31], s[4:5], v20, s84, v[18:19]
	global_load_dwordx4 v[10:13], v[14:15], off offset:128
	s_nop 0
	global_load_dwordx4 v[14:17], v[14:15], off offset:192
	s_nop 0
	global_load_dwordx4 v[18:21], v[30:31], off
	global_load_dwordx4 v[22:25], v[30:31], off offset:64
	global_load_dwordx4 v[26:29], v[30:31], off offset:128
	s_nop 0
	global_load_dwordx4 v[30:33], v[30:31], off offset:192
	s_mul_hi_i32 s7, s11, 0x3388000
	s_mul_i32 s11, s11, 0x3388000
	s_add_u32 s4, s1, s11
	s_addc_u32 s5, s16, s7
	s_add_u32 s12, s4, s12
	s_addc_u32 s13, s5, 0
	s_add_u32 s4, s12, s6
	s_addc_u32 s5, s13, 0
	s_add_u32 s4, s4, 0x2000
	s_addc_u32 s5, s5, 0
	s_add_u32 s12, s12, 0x2800
	s_addc_u32 s13, s13, 0
	v_and_b32_e32 v36, 0x3fffffc0, v37
	s_add_i32 s33, 0, 0x20800
	v_ashrrev_i32_e32 v49, 31, v37
	v_lshl_add_u32 v45, v36, 2, s33
	v_lshrrev_b32_e32 v36, 27, v49
	v_add_u32_e32 v36, v37, v36
	v_ashrrev_i32_e32 v52, 5, v36
	v_and_b32_e32 v36, 0xfffffe0, v36
	v_sub_u32_e32 v36, v37, v36
	v_lshlrev_b32_e32 v36, 4, v36
	v_add_u32_e32 v53, 0x200, v37
	v_mad_u64_u32 v[38:39], s[36:37], v52, s84, v[36:37]
	v_ashrrev_i32_e32 v54, 31, v53
	v_lshrrev_b32_e32 v39, 27, v54
	v_add_u32_e32 v39, v53, v39
	v_ashrrev_i32_e32 v55, 5, v39
	v_and_b32_e32 v39, 0xfffffe0, v39
	v_sub_u32_e32 v39, v53, v39
	v_lshlrev_b32_e32 v41, 13, v187
	v_lshlrev_b32_e32 v40, 4, v39
	v_mad_u64_u32 v[42:43], s[36:37], v55, s84, v[40:41]
	v_add_u32_e32 v39, 0x400, v37
	v_ashrrev_i32_e32 v43, 31, v39
	v_lshrrev_b32_e32 v43, 27, v43
	v_add_u32_e32 v43, v39, v43
	v_ashrrev_i32_e32 v56, 5, v43
	v_and_b32_e32 v43, 0xfffffe0, v43
	v_sub_u32_e32 v39, v39, v43
	v_lshlrev_b32_e32 v44, 4, v39
	v_add_u32_e32 v39, 0x600, v37
	v_ashrrev_i32_e32 v43, 31, v39
	v_lshrrev_b32_e32 v43, 27, v43
	v_add_u32_e32 v43, v39, v43
	v_ashrrev_i32_e32 v57, 5, v43
	v_and_b32_e32 v43, 0xfffffe0, v43
	v_lshrrev_b32_e32 v35, 4, v37
	s_add_i32 s30, 0, 0x10800
	v_sub_u32_e32 v39, v39, v43
	v_lshlrev_b32_e32 v214, 8, v253
	v_and_b32_e32 v43, 7, v37
	v_add3_u32 v41, s30, v41, v214
	v_bitop3_b32 v35, v35, v43, 3 bitop3:0x6c
	v_lshlrev_b32_e32 v48, 4, v39
	v_lshlrev_b32_e32 v39, 4, v37
	v_lshl_add_u32 v35, v35, 4, v41
	global_load_dwordx4 v[66:69], v38, s[12:13]
	global_load_dwordx4 v[70:73], v42, s[12:13]
	v_and_b32_e32 v39, 0x70, v39
	v_mad_u64_u32 v[46:47], s[36:37], v56, s84, v[44:45]
	v_mad_u64_u32 v[50:51], s[36:37], v57, s84, v[48:49]
	global_load_dwordx4 v[74:77], v46, s[12:13]
	global_load_dwordx4 v[78:81], v50, s[12:13]
	s_cmp_lg_u32 0, -1
	s_cselect_b32 s12, 0, 0
	v_readfirstlane_b32 s13, v187
	s_lshl_b32 s33, s13, 10
	s_add_i32 s30, 0, 0x8800
	s_cmp_lg_u32 s30, -1
	s_waitcnt vmcnt(11)
	ds_write_b128 v35, v[2:5]
	v_or_b32_e32 v2, 64, v34
	v_or_b32_e32 v3, 0x80, v34
	v_or_b32_e32 v4, 0xc0, v34
	v_xad_u32 v2, v2, v39, v41
	v_xad_u32 v3, v3, v39, v41
	v_xad_u32 v4, v4, v39, v41
	s_waitcnt vmcnt(10)
	ds_write_b128 v2, v[6:9]
	s_waitcnt vmcnt(9)
	ds_write_b128 v3, v[10:13]
	s_waitcnt vmcnt(8)
	ds_write_b128 v4, v[14:17]
	s_waitcnt vmcnt(7)
	ds_write_b128 v35, v[18:21] offset:4096
	s_waitcnt vmcnt(6)
	ds_write_b128 v2, v[22:25] offset:4096
	s_waitcnt vmcnt(5)
	ds_write_b128 v3, v[26:29] offset:4096
	s_waitcnt vmcnt(4)
; #define SBAR() __builtin_amdgcn_sched_barrier(0)
; #define SWRITE(b, i) do { *(bf16x8*)(V_lds + (b) * SHM_V + vst0) = sr_[i].vs0; *(bf16x8*)(V_lds + (b) * SHM_V + vst1) = sr_[i].vs1; \
;     _Pragma("unroll") for (int _q = 0; _q < KP; ++_q) *(bf16x8*)(K_lds + (b) * SHM_K + KROW(_q) * (DK * 2) + ((KC8(_q) * 16) ^ ((KROW(_q) & 7) << 4))) = sr_[i].ks[_q]; } while (0)
; #define SWAIT() do { if constexpr (SDEPTH == 2) asm volatile("s_waitcnt vmcnt(4)" ::: "memory"); else asm volatile("s_waitcnt vmcnt(0)" ::: "memory"); } while (0)
; #define SWRITE(b) SWRITE2(b, b)
; template <int DK, int DV, int LDQ, int LDK, int LDV, int LDO, typename TOut, bool PIPE, bool QL, bool VS>
; __device__ __forceinline__ void attn_body16(const bf16_t* Qb, const bf16_t* Kh, const bf16_t* Vh, TOut* Ob, int seq, char* lds) {
;     ...
;   const int vb0 = (int)(uintptr_t)V_lds + (4 * g + (c >> 2)) * VRSB + (c & 3) * 8;
;   struct { bf16x8 vs[VP], ks[PIPE ? KP : 1]; } sr_;
;   const int widu = __builtin_amdgcn_readfirstlane(wid);
;     ...
;   bf16x8 pa[2][2]; const int NT = seq / KVBLK;
;   if constexpr (PIPE) {
;     f32x4 sA[4][2], sB[4][2]; float alA[2], alB[2];
;     SLOAD(0); asm volatile("s_waitcnt vmcnt(0)" ::: "memory"); SWRITE(0); __syncthreads();
;     QKT(sA, K_lds); partialSM16(sA, m_reg, alA, C, THR_S);
;     SLOAD(KVBLK);
;     SWAIT(); SWRITE(1); __syncthreads();
;     for (int j = 1; j + 1 < NT; j += 2) {
;       SLOAD((j + 1) * KVBLK); SBAR(); QKT(sB, K_lds + SHM_K); SBAR();
;       finishSM16(sA, alA, lp, pa); SBAR();
;       pv16<NVT, VRSB>(o, vb0, pa); partialSM16(sB, m_reg, alB, C, THR_S);
;       __syncthreads(); SWAIT(); SWRITE(0);
;       RESC(alB); __syncthreads();
;       SLOAD((j + 2) * KVBLK); SBAR(); QKT(sA, K_lds); SBAR();
;       finishSM16(sB, alB, lp, pa); SBAR();
;       pv16<NVT, VRSB>(o, vb0 + (int)SHM_V, pa); partialSM16(sA, m_reg, alA, C, THR_S);
;       __syncthreads(); SWAIT(); SWRITE(1);
;       RESC(alA); __syncthreads();
;     }
;     SBAR(); QKT(sB, K_lds + SHM_K); SBAR();
;     finishSM16(sA, alA, lp, pa); SBAR();
;     pv16<NVT, VRSB>(o, vb0, pa); partialSM16(sB, m_reg, alB, C, THR_S);
;     __syncthreads(); RESC(alB);
;     finishSM16(sB, alB, lp, pa); SBAR();
;     pv16<NVT, VRSB>(o, vb0 + (int)SHM_V, pa);
;   } else {
;     f32x4 s[4][2]; float al[2];
;     VLOAD(0); KDMA(0, 0); asm volatile("s_waitcnt vmcnt(0)" ::: "memory"); VWRITE(0); __syncthreads();
	ds_write_b128 v4, v[30:33] offset:4096
	v_bfe_u32 v2, v37, 2, 2
	v_lshl_or_b32 v2, v252, 2, v2
	v_lshlrev_b32_e32 v3, 3, v37
	v_and_b32_e32 v3, 24, v3
	v_mul_u32_u24_e32 v2, 0x220, v2
	v_add3_u32 v216, v3, s12, v2
	v_lshrrev_b32_e32 v2, 28, v49
	v_add_u32_e32 v2, v37, v2
	v_lshrrev_b32_e32 v4, 28, v54
	v_ashrrev_i32_e32 v3, 4, v2
	v_and_b32_e32 v2, 0xffffff0, v2
	v_add_u32_e32 v4, v53, v4
	s_cselect_b32 s12, s30, 0
	v_sub_u32_e32 v2, v37, v2
	v_ashrrev_i32_e32 v5, 4, v4
	v_and_b32_e32 v4, 0xffffff0, v4
	s_add_i32 s33, s33, s12
	v_bitop3_b32 v2, v3, v2, 7 bitop3:0x6c
	v_mul_lo_u32 v3, v3, s84
	v_sub_u32_e32 v4, v53, v4
	v_lshl_add_u32 v2, v2, 4, v3
	s_mov_b32 m0, s33
	v_bitop3_b32 v4, v5, v4, 7 bitop3:0x6c
	v_mul_lo_u32 v5, v5, s84
	global_load_lds_dwordx4 v2, s[4:5]
	v_lshl_add_u32 v4, v4, 4, v5
	s_add_i32 m0, s33, 0x2000
	v_mul_lo_u32 v6, v52, s86
	global_load_lds_dwordx4 v4, s[4:5]
	v_add_u32_e32 v6, 0, v6
	v_add_u32_e32 v217, v6, v36
	v_mul_lo_u32 v6, v55, s86
	v_add_u32_e32 v6, 0, v6
	s_lshl_b32 s10, s10, 8
	v_add_u32_e32 v218, v6, v40
	v_mul_lo_u32 v6, v56, s86
	s_and_b32 s10, s10, 0x600
	v_add_u32_e32 v6, 0, v6
	s_or_b32 s12, s11, s10
	v_add_u32_e32 v220, v6, v44
	v_mul_lo_u32 v6, v57, s86
	s_add_u32 s10, s21, s12
	v_add_u32_e32 v6, 0, v6
	v_lshlrev_b32_e32 v178, 4, v253
	s_movk_i32 s4, 0x70
	s_addc_u32 s11, s22, s7
	s_or_b32 s6, s12, s6
	v_add_u32_e32 v221, v6, v48
	v_and_b32_e32 v6, 0x70, v178
	v_bitop3_b32 v222, v34, v178, s4 bitop3:0x78
	s_movk_i32 s4, 0xc0
	s_add_u32 s6, s23, s6
	v_mov_b32_e32 v39, v179
	v_mov_b32_e32 v43, v179
	v_mov_b32_e32 v47, v179
	v_mov_b32_e32 v51, v179
	v_mov_b32_e32 v3, v179
	v_mov_b32_e32 v5, v179
	s_waitcnt vmcnt(0)
	v_bitop3_b32 v224, v34, v6, 64 bitop3:0x36
	v_bitop3_b32 v226, v34, v6, s14 bitop3:0x36
	v_bitop3_b32 v228, v34, v6, s4 bitop3:0x36
	s_addc_u32 s7, s24, s7
	v_mov_b32_e32 v18, v179
	v_mov_b32_e32 v19, v179
	v_mov_b32_e32 v20, v179
	v_mov_b32_e32 v21, v179
	v_add_u32_e32 v223, v41, v222
	v_add_u32_e32 v225, v41, v224
	v_add_u32_e32 v227, v41, v226
	v_add_u32_e32 v229, v41, v228
	v_lshl_add_u32 v219, v253, 2, v45
	v_add_u32_e32 v215, v45, v34
	s_mov_b64 s[56:57], s[10:11]
	s_mov_b64 s[58:59], s[6:7]
	v_mov_b32_e32 v188, v38
	v_mov_b32_e32 v190, v42
	v_mov_b32_e32 v192, v46
	v_mov_b32_e32 v194, v50
	v_mov_b32_e32 v198, v2
	v_mov_b32_e32 v200, v4
	v_mov_b32_e32 v196, 0
	v_mov_b64_e32 v[84:85], v[20:21]
	v_mov_b64_e32 v[88:89], v[20:21]
	v_mov_b64_e32 v[92:93], v[20:21]
	v_mov_b64_e32 v[96:97], v[20:21]
	v_mov_b64_e32 v[100:101], v[20:21]
	v_mov_b64_e32 v[104:105], v[20:21]
	v_mov_b64_e32 v[108:109], v[20:21]
	v_mov_b64_e32 v[112:113], v[20:21]
	v_mov_b64_e32 v[36:37], v[20:21]
	v_mov_b64_e32 v[40:41], v[20:21]
	v_mov_b64_e32 v[44:45], v[20:21]
	v_mov_b64_e32 v[48:49], v[20:21]
	v_mov_b64_e32 v[52:53], v[20:21]
	v_mov_b64_e32 v[56:57], v[20:21]
	v_mov_b64_e32 v[60:61], v[20:21]
	v_mov_b64_e32 v[64:65], v[20:21]
	v_mov_b64_e32 v[116:117], v[20:21]
	v_mov_b64_e32 v[120:121], v[20:21]
	v_mov_b64_e32 v[124:125], v[20:21]
	v_mov_b64_e32 v[128:129], v[20:21]
	v_mov_b64_e32 v[132:133], v[20:21]
	v_mov_b64_e32 v[136:137], v[20:21]
	v_mov_b64_e32 v[140:141], v[20:21]
	v_mov_b64_e32 v[144:145], v[20:21]
	v_mov_b64_e32 v[32:33], v[20:21]
	v_mov_b64_e32 v[28:29], v[20:21]
	v_mov_b64_e32 v[24:25], v[20:21]
	v_mov_b64_e32 v[14:15], v[18:19]
	v_mov_b64_e32 v[10:11], v[18:19]
	v_mov_b64_e32 v[6:7], v[18:19]
	v_mov_b64_e32 v[2:3], v[18:19]
	s_mov_b32 s29, 1
	v_cmp_eq_u32_e64 s[4:5], 0, v252
	v_mov_b32_e32 v230, 0xf149f2ca
	s_mov_b64 s[10:11], 0
	v_mov_b64_e32 v[82:83], v[18:19]
	v_mov_b64_e32 v[86:87], v[18:19]
	v_mov_b64_e32 v[90:91], v[18:19]
	v_mov_b64_e32 v[94:95], v[18:19]
	v_mov_b64_e32 v[98:99], v[18:19]
	v_mov_b64_e32 v[102:103], v[18:19]
	v_mov_b64_e32 v[106:107], v[18:19]
	v_mov_b64_e32 v[110:111], v[18:19]
	v_mov_b64_e32 v[34:35], v[18:19]
	v_mov_b64_e32 v[38:39], v[18:19]
	v_mov_b64_e32 v[42:43], v[18:19]
	v_mov_b64_e32 v[46:47], v[18:19]
	v_mov_b64_e32 v[50:51], v[18:19]
	v_mov_b64_e32 v[54:55], v[18:19]
	v_mov_b64_e32 v[58:59], v[18:19]
	v_mov_b64_e32 v[62:63], v[18:19]
	v_mov_b64_e32 v[114:115], v[18:19]
	v_mov_b64_e32 v[118:119], v[18:19]
	v_mov_b64_e32 v[122:123], v[18:19]
	v_mov_b64_e32 v[126:127], v[18:19]
	v_mov_b64_e32 v[130:131], v[18:19]
	v_mov_b64_e32 v[134:135], v[18:19]
	v_mov_b64_e32 v[138:139], v[18:19]
	v_mov_b64_e32 v[142:143], v[18:19]
	v_mov_b64_e32 v[30:31], v[18:19]
	v_mov_b64_e32 v[26:27], v[18:19]
	v_mov_b64_e32 v[22:23], v[18:19]
	v_mov_b64_e32 v[16:17], v[20:21]
	v_mov_b64_e32 v[12:13], v[20:21]
	v_mov_b64_e32 v[8:9], v[20:21]
	v_mov_b64_e32 v[4:5], v[20:21]
	v_mov_b32_e32 v231, 0xf149f2ca
	v_mov_b32_e32 v197, v196
	s_waitcnt vmcnt(0)
	ds_write_b128 v217, v[66:69]
	ds_write_b128 v218, v[70:73]
	ds_write_b128 v220, v[74:77]
	ds_write_b128 v221, v[78:81]
	s_waitcnt lgkmcnt(0)
	s_barrier
	s_mov_b32 s64, 0x3e0293ee
	s_branch .LBB0_700

; #define SBAR() __builtin_amdgcn_sched_barrier(0)
; #define RESC(a) do { if (__any((a) < 1.f)) { if (hi == 0) al_l[r32] = (a); asm volatile("s_waitcnt lgkmcnt(0)" ::: "memory"); \
;     _Pragma("unroll") for (int d = 0; d < 4; ++d) _Pragma("unroll") for (int r = 0; r < 16; ++r) o[d][r] *= al_l[crow(r, hi)]; } } while (0)
; template <int NVT, int VRSB, int KB, int DH, int VT> __device__ __forceinline__ void pvh_pro(int vb, s16x4 (&f)[DH + 1][2]) { if constexpr (VT < DH && VT < NVT) { pvh_ld<VT, KB, VRSB>(f[VT], vb); pvh_pro<NVT, VRSB, KB, DH, VT + 1>(vb, f); } }
; __device__ __forceinline__ void partialSM16(f32x4 (&s)[4][2], float (&m_reg)[2], float (&alpha)[2], const float C, const float thr_s) {
;     ...
;   for (int qt = 0; qt < 2; ++qt) { const float mnC = -mn[qt] * C;
; #pragma unroll
;     for (int kt = 0; kt < 4; ++kt)
; #pragma unroll
;       for (int r = 0; r < 4; ++r) s[kt][qt][r] = fmaf(s[kt][qt][r], C, mnC); }
; #pragma unroll
;   for (int qt = 0; qt < 2; ++qt)
; #pragma unroll
;     for (int kt = 0; kt < 2; ++kt)
; #pragma unroll
;       for (int r = 0; r < 4; ++r) s[kt][qt][r] = __builtin_amdgcn_exp2f(s[kt][qt][r]);
; template <int DK, int DV, int LDQ, int LDK, int LDV, int LDO, typename TOut, bool PIPE, bool QL, bool VS>
; __device__ __forceinline__ void attn_body16(const bf16_t* Qb, const bf16_t* Kh, const bf16_t* Vh, TOut* Ob, int seq, char* lds) {
;     ...
;       partialSM16(s, m_reg, al, C, THR_S);
;       RESC(al);
;       constexpr int DH = 3; s16x4 pvf[DH + 1][2]; const int vbt = vb0 + vsel * (int)SHM_V;
;       pvh_pro<NVT, VRSB, 0, DH, 0>(vbt, pvf); SBAR();
;       cvt_pa(s, pa, 0); SBAR();
;       pvh_step<NVT, VRSB, 0, DH, true, 0>(o, vbt, pa, pvf, s);
.LBB0_710:
	v_mul_f32_e32 v1, 0xbe0293ee, v231
	v_fmamk_f32 v208, v170, 0x3e0293ee, v1
	v_fmamk_f32 v212, v171, 0x3e0293ee, v1
	ds_read_b64_tr_b16 v[170:171], v216 offset:0
	v_fmamk_f32 v213, v172, 0x3e0293ee, v1
	v_fmamk_f32 v236, v173, 0x3e0293ee, v1
	ds_read_b64_tr_b16 v[172:173], v216 offset:0x2200
	v_fmamk_f32 v240, v174, 0x3e0293ee, v1
	v_fmamk_f32 v244, v175, 0x3e0293ee, v1
	v_mul_f32_e32 v246, 0xbe0293ee, v230
	ds_read_b64_tr_b16 v[174:175], v216 offset:32
	v_fmamk_f32 v162, v162, 0x3e0293ee, v1
	v_fmamk_f32 v163, v163, 0x3e0293ee, v1
	v_fmamk_f32 v164, v164, 0x3e0293ee, v1
	v_fmamk_f32 v165, v165, 0x3e0293ee, v1
	v_fmamk_f32 v182, v166, 0x3e0293ee, v1
	v_fmamk_f32 v167, v167, 0x3e0293ee, v1
	v_fmamk_f32 v183, v168, 0x3e0293ee, v1
	v_fmamk_f32 v169, v169, 0x3e0293ee, v1
	v_fmamk_f32 v245, v176, 0x3e0293ee, v1
	v_fmac_f32_e32 v1, 0x3e0293ee, v177
	v_pk_fma_f32 v[146:147], v[146:147], s[64:65], v[246:247] op_sel_hi:[1,0,0]
	v_pk_fma_f32 v[148:149], v[148:149], s[64:65], v[246:247] op_sel_hi:[1,0,0]
	v_pk_fma_f32 v[150:151], v[150:151], s[64:65], v[246:247] op_sel_hi:[1,0,0]
	v_pk_fma_f32 v[152:153], v[152:153], s[64:65], v[246:247] op_sel_hi:[1,0,0]
	ds_read_b64_tr_b16 v[176:177], v216 offset:0x2220
	v_fmamk_f32 v237, v154, 0x3e0293ee, v246
	v_fmamk_f32 v238, v155, 0x3e0293ee, v246
	v_fmamk_f32 v239, v156, 0x3e0293ee, v246
	v_fmamk_f32 v241, v157, 0x3e0293ee, v246
	v_fmamk_f32 v247, v158, 0x3e0293ee, v246
	v_fmamk_f32 v248, v159, 0x3e0293ee, v246
	v_fmamk_f32 v249, v160, 0x3e0293ee, v246
	v_fmac_f32_e32 v246, 0x3e0293ee, v161
	v_exp_f32_e32 v166, v162
	v_exp_f32_e32 v168, v163
	v_exp_f32_e32 v162, v164
	v_exp_f32_e32 v164, v165
	v_exp_f32_e32 v158, v182
	v_exp_f32_e32 v160, v167
	v_exp_f32_e32 v154, v183
	v_exp_f32_e32 v156, v169
	v_exp_f32_e32 v167, v146
	v_exp_f32_e32 v169, v147
	v_exp_f32_e32 v163, v148
	v_exp_f32_e32 v165, v149
	v_exp_f32_e32 v159, v150
	v_exp_f32_e32 v161, v151
	v_exp_f32_e32 v155, v152
	v_exp_f32_e32 v157, v153
	ds_read_b64_tr_b16 v[182:183], v216 offset:64
	ds_read_b64_tr_b16 v[184:185], v216 offset:0x2240
	s_mov_b64 s[36:37], s[74:75]
	v_cvt_pk_bf16_f32 v146, v166, v168
	v_cvt_pk_bf16_f32 v147, v162, v164
	v_cvt_pk_bf16_f32 v148, v158, v160
	v_cvt_pk_bf16_f32 v149, v154, v156
	v_cvt_pk_bf16_f32 v150, v167, v169
	v_cvt_pk_bf16_f32 v151, v163, v165
	v_cvt_pk_bf16_f32 v152, v159, v161
	v_cvt_pk_bf16_f32 v153, v155, v157
	ds_read_b64_tr_b16 v[204:205], v216 offset:0x60
	ds_read_b64_tr_b16 v[206:207], v216 offset:0x2260
	s_waitcnt lgkmcnt(6)
	v_mfma_f32_16x16x32_bf16 v[142:145], v[146:149], v[170:173], v[142:145]
	s_nop 0
	v_mfma_f32_16x16x32_bf16 v[110:113], v[150:153], v[170:173], v[110:113]
	v_exp_f32_e32 v170, v208
	ds_read_b64_tr_b16 v[208:209], v216 offset:0x80
	ds_read_b64_tr_b16 v[210:211], v216 offset:0x2280
	s_waitcnt lgkmcnt(6)
	v_mfma_f32_16x16x32_bf16 v[138:141], v[146:149], v[174:177], v[138:141]
	v_exp_f32_e32 v172, v212
	v_mfma_f32_16x16x32_bf16 v[106:109], v[150:153], v[174:177], v[106:109]
	ds_read_b64_tr_b16 v[232:233], v216 offset:0xa0
	ds_read_b64_tr_b16 v[234:235], v216 offset:0x22a0
	s_waitcnt lgkmcnt(6)
	v_mfma_f32_16x16x32_bf16 v[134:137], v[146:149], v[182:185], v[134:137]
	v_exp_f32_e32 v174, v213
	v_mfma_f32_16x16x32_bf16 v[102:105], v[150:153], v[182:185], v[102:105]
	ds_read_b64_tr_b16 v[182:183], v216 offset:0xc0
	ds_read_b64_tr_b16 v[184:185], v216 offset:0x22c0
	s_waitcnt lgkmcnt(6)
	v_mfma_f32_16x16x32_bf16 v[130:133], v[146:149], v[204:207], v[130:133]
	v_exp_f32_e32 v176, v236
	v_mfma_f32_16x16x32_bf16 v[98:101], v[150:153], v[204:207], v[98:101]
	ds_read_b64_tr_b16 v[204:205], v216 offset:0xe0
	ds_read_b64_tr_b16 v[206:207], v216 offset:0x22e0
	s_waitcnt lgkmcnt(6)
	v_mfma_f32_16x16x32_bf16 v[126:129], v[146:149], v[208:211], v[126:129]
	v_exp_f32_e32 v171, v237
	v_mfma_f32_16x16x32_bf16 v[94:97], v[150:153], v[208:211], v[94:97]
	ds_read_b64_tr_b16 v[208:209], v216 offset:0x100
	ds_read_b64_tr_b16 v[210:211], v216 offset:0x2300
	s_waitcnt lgkmcnt(6)
	v_mfma_f32_16x16x32_bf16 v[122:125], v[146:149], v[232:235], v[122:125]
	v_exp_f32_e32 v173, v238
	v_mfma_f32_16x16x32_bf16 v[90:93], v[150:153], v[232:235], v[90:93]
	ds_read_b64_tr_b16 v[232:233], v216 offset:0x120
	ds_read_b64_tr_b16 v[234:235], v216 offset:0x2320
	s_waitcnt lgkmcnt(6)
	v_mfma_f32_16x16x32_bf16 v[118:121], v[146:149], v[182:185], v[118:121]
	v_exp_f32_e32 v175, v239
	v_mfma_f32_16x16x32_bf16 v[86:89], v[150:153], v[182:185], v[86:89]
	ds_read_b64_tr_b16 v[182:183], v216 offset:0x140
	ds_read_b64_tr_b16 v[184:185], v216 offset:0x2340
	s_waitcnt lgkmcnt(6)
	v_mfma_f32_16x16x32_bf16 v[114:117], v[146:149], v[204:207], v[114:117]
	v_exp_f32_e32 v177, v241
	v_mfma_f32_16x16x32_bf16 v[82:85], v[150:153], v[204:207], v[82:85]
	ds_read_b64_tr_b16 v[236:237], v216 offset:0x160
	ds_read_b64_tr_b16 v[238:239], v216 offset:0x2360
	s_waitcnt lgkmcnt(6)
	v_mfma_f32_16x16x32_bf16 v[62:65], v[146:149], v[208:211], v[62:65]
	v_exp_f32_e32 v204, v240
	v_mfma_f32_16x16x32_bf16 v[18:21], v[150:153], v[208:211], v[18:21]
	ds_read_b64_tr_b16 v[240:241], v216 offset:0x180
	ds_read_b64_tr_b16 v[242:243], v216 offset:0x2380
	s_waitcnt lgkmcnt(6)
	v_mfma_f32_16x16x32_bf16 v[58:61], v[146:149], v[232:235], v[58:61]
	v_exp_f32_e32 v206, v244
	v_mfma_f32_16x16x32_bf16 v[30:33], v[150:153], v[232:235], v[30:33]
	ds_read_b64_tr_b16 v[232:233], v216 offset:0x1a0
	ds_read_b64_tr_b16 v[234:235], v216 offset:0x23a0
	s_waitcnt lgkmcnt(6)
	v_mfma_f32_16x16x32_bf16 v[54:57], v[146:149], v[182:185], v[54:57]
	v_exp_f32_e32 v208, v245
	v_mfma_f32_16x16x32_bf16 v[26:29], v[150:153], v[182:185], v[26:29]
	ds_read_b64_tr_b16 v[182:183], v216 offset:0x1c0
	ds_read_b64_tr_b16 v[184:185], v216 offset:0x23c0
	s_waitcnt lgkmcnt(6)
; #define SBAR() __builtin_amdgcn_sched_barrier(0)
; template <int NVT, int VRSB, int KB, int DH, int VT> __device__ __forceinline__ void pvh_pro(int vb, s16x4 (&f)[DH + 1][2]) { if constexpr (VT < DH && VT < NVT) { pvh_ld<VT, KB, VRSB>(f[VT], vb); pvh_pro<NVT, VRSB, KB, DH, VT + 1>(vb, f); } }
; #define VWRITE(bv) do { _Pragma("unroll") for (int _q = 0; _q < VP; ++_q) *(bf16x8*)(V_lds + (bv) * SHM_V + VROW(_q) * VRSB + VC8(_q) * 16) = sr_.vs[_q]; } while (0)
; template <int DK, int DV, int LDQ, int LDK, int LDV, int LDO, typename TOut, bool PIPE, bool QL, bool VS>
; __device__ __forceinline__ void attn_body16(const bf16_t* Qb, const bf16_t* Kh, const bf16_t* Vh, TOut* Ob, int seq, char* lds) {
;     ...
;       pvh_step<NVT, VRSB, 0, DH, true, 0>(o, vbt, pa, pvf, s);
;       pvh_pro<NVT, VRSB, 1, DH, 0>(vbt, pvf); SBAR();
; #pragma unroll
;       for (int qt = 0; qt < 2; ++qt) { float ps = 0.f;
; #pragma unroll
;         for (int kt = 0; kt < 4; ++kt) ps += (s[kt][qt][0] + s[kt][qt][1]) + (s[kt][qt][2] + s[kt][qt][3]);
;         lp[qt] = lp[qt] * al[qt] + ps; }
;       cvt_pa(s, pa, 1); SBAR();
;       pvh_step<NVT, VRSB, 1, DH, false, 0>(o, vbt, pa, pvf, s);
;       if constexpr (VS) {
;         asm volatile("s_waitcnt vmcnt(0)" ::: "memory");
;         __syncthreads();
;         if (j + 1 < NT) VWRITE(0);
;       } else if (j + 1 < NT) { asm volatile("s_waitcnt vmcnt(0)" ::: "memory"); VWRITE(bsel ^ 1); }
;       __syncthreads();
	v_mfma_f32_16x16x32_bf16 v[50:53], v[146:149], v[236:239], v[50:53]
	v_exp_f32_e32 v210, v1
	v_mfma_f32_16x16x32_bf16 v[22:25], v[150:153], v[236:239], v[22:25]
	ds_read_b64_tr_b16 v[236:237], v216 offset:0x1e0
	ds_read_b64_tr_b16 v[238:239], v216 offset:0x23e0
	s_waitcnt lgkmcnt(6)
	v_mfma_f32_16x16x32_bf16 v[46:49], v[146:149], v[240:243], v[46:49]
	v_exp_f32_e32 v205, v247
	v_mfma_f32_16x16x32_bf16 v[14:17], v[150:153], v[240:243], v[14:17]
	s_waitcnt lgkmcnt(4)
	v_mfma_f32_16x16x32_bf16 v[42:45], v[146:149], v[232:235], v[42:45]
	v_exp_f32_e32 v207, v248
	v_mfma_f32_16x16x32_bf16 v[10:13], v[150:153], v[232:235], v[10:13]
	s_waitcnt lgkmcnt(2)
	v_mfma_f32_16x16x32_bf16 v[38:41], v[146:149], v[182:185], v[38:41]
	v_exp_f32_e32 v209, v249
	v_mfma_f32_16x16x32_bf16 v[6:9], v[150:153], v[182:185], v[6:9]
	s_waitcnt lgkmcnt(0)
	v_mfma_f32_16x16x32_bf16 v[34:37], v[146:149], v[236:239], v[34:37]
	v_exp_f32_e32 v211, v246
	v_mfma_f32_16x16x32_bf16 v[2:5], v[150:153], v[236:239], v[2:5]
	ds_read_b64_tr_b16 v[146:147], v216 offset:0x4400
	ds_read_b64_tr_b16 v[148:149], v216 offset:0x6600
	ds_read_b64_tr_b16 v[150:151], v216 offset:0x4420
	ds_read_b64_tr_b16 v[152:153], v216 offset:0x6620
	ds_read_b64_tr_b16 v[182:183], v216 offset:0x4440
	ds_read_b64_tr_b16 v[184:185], v216 offset:0x6640
	v_cvt_pk_bf16_f32 v232, v170, v172
	v_cvt_pk_bf16_f32 v233, v174, v176
	v_cvt_pk_bf16_f32 v234, v204, v206
	v_cvt_pk_bf16_f32 v235, v208, v210
	v_cvt_pk_bf16_f32 v236, v171, v173
	v_cvt_pk_bf16_f32 v237, v175, v177
	v_cvt_pk_bf16_f32 v238, v205, v207
	v_cvt_pk_bf16_f32 v239, v209, v211
	ds_read_b64_tr_b16 v[240:241], v216 offset:0x4460
	ds_read_b64_tr_b16 v[242:243], v216 offset:0x6660
	s_waitcnt lgkmcnt(6)
	v_mfma_f32_16x16x32_bf16 v[142:145], v[232:235], v[146:149], v[142:145]
	s_nop 0
	v_mfma_f32_16x16x32_bf16 v[110:113], v[236:239], v[146:149], v[110:113]
	ds_read_b64_tr_b16 v[146:147], v216 offset:0x4480
	ds_read_b64_tr_b16 v[148:149], v216 offset:0x6680
	s_waitcnt lgkmcnt(6)
	v_mfma_f32_16x16x32_bf16 v[138:141], v[232:235], v[150:153], v[138:141]
	v_mfma_f32_16x16x32_bf16 v[106:109], v[236:239], v[150:153], v[106:109]
	ds_read_b64_tr_b16 v[150:151], v216 offset:0x44a0
	ds_read_b64_tr_b16 v[152:153], v216 offset:0x66a0
	s_waitcnt lgkmcnt(6)
	v_mfma_f32_16x16x32_bf16 v[134:137], v[232:235], v[182:185], v[134:137]
	v_mfma_f32_16x16x32_bf16 v[102:105], v[236:239], v[182:185], v[102:105]
	ds_read_b64_tr_b16 v[182:183], v216 offset:0x44c0
	ds_read_b64_tr_b16 v[184:185], v216 offset:0x66c0
	s_waitcnt lgkmcnt(6)
	v_mfma_f32_16x16x32_bf16 v[130:133], v[232:235], v[240:243], v[130:133]
	v_mfma_f32_16x16x32_bf16 v[98:101], v[236:239], v[240:243], v[98:101]
	ds_read_b64_tr_b16 v[240:241], v216 offset:0x44e0
	ds_read_b64_tr_b16 v[242:243], v216 offset:0x66e0
	s_waitcnt lgkmcnt(6)
	v_mfma_f32_16x16x32_bf16 v[126:129], v[232:235], v[146:149], v[126:129]
	v_mfma_f32_16x16x32_bf16 v[94:97], v[236:239], v[146:149], v[94:97]
	ds_read_b64_tr_b16 v[146:147], v216 offset:0x4500
	ds_read_b64_tr_b16 v[148:149], v216 offset:0x6700
	s_waitcnt lgkmcnt(6)
	v_mfma_f32_16x16x32_bf16 v[122:125], v[232:235], v[150:153], v[122:125]
	v_mfma_f32_16x16x32_bf16 v[90:93], v[236:239], v[150:153], v[90:93]
	ds_read_b64_tr_b16 v[150:151], v216 offset:0x4520
	ds_read_b64_tr_b16 v[152:153], v216 offset:0x6720
	s_waitcnt lgkmcnt(6)
	v_mfma_f32_16x16x32_bf16 v[118:121], v[232:235], v[182:185], v[118:121]
	v_mfma_f32_16x16x32_bf16 v[86:89], v[236:239], v[182:185], v[86:89]
	ds_read_b64_tr_b16 v[182:183], v216 offset:0x4540
	ds_read_b64_tr_b16 v[184:185], v216 offset:0x6740
	s_waitcnt lgkmcnt(6)
	v_mfma_f32_16x16x32_bf16 v[114:117], v[232:235], v[240:243], v[114:117]
	v_mfma_f32_16x16x32_bf16 v[82:85], v[236:239], v[240:243], v[82:85]
	ds_read_b64_tr_b16 v[240:241], v216 offset:0x4560
	ds_read_b64_tr_b16 v[242:243], v216 offset:0x6760
	s_waitcnt lgkmcnt(6)
	v_mfma_f32_16x16x32_bf16 v[62:65], v[232:235], v[146:149], v[62:65]
	v_mfma_f32_16x16x32_bf16 v[18:21], v[236:239], v[146:149], v[18:21]
	ds_read_b64_tr_b16 v[146:147], v216 offset:0x4580
	ds_read_b64_tr_b16 v[148:149], v216 offset:0x6780
	s_waitcnt lgkmcnt(6)
	v_mfma_f32_16x16x32_bf16 v[58:61], v[232:235], v[150:153], v[58:61]
	v_mfma_f32_16x16x32_bf16 v[30:33], v[236:239], v[150:153], v[30:33]
	ds_read_b64_tr_b16 v[150:151], v216 offset:0x45a0
	ds_read_b64_tr_b16 v[152:153], v216 offset:0x67a0
	s_waitcnt lgkmcnt(6)
	v_mfma_f32_16x16x32_bf16 v[54:57], v[232:235], v[182:185], v[54:57]
	v_mfma_f32_16x16x32_bf16 v[26:29], v[236:239], v[182:185], v[26:29]
	ds_read_b64_tr_b16 v[182:183], v216 offset:0x45c0
	ds_read_b64_tr_b16 v[184:185], v216 offset:0x67c0
	s_waitcnt lgkmcnt(6)
	v_mfma_f32_16x16x32_bf16 v[50:53], v[232:235], v[240:243], v[50:53]
	v_mfma_f32_16x16x32_bf16 v[22:25], v[236:239], v[240:243], v[22:25]
	ds_read_b64_tr_b16 v[240:241], v216 offset:0x45e0
	ds_read_b64_tr_b16 v[242:243], v216 offset:0x67e0
	s_waitcnt lgkmcnt(6)
	v_mfma_f32_16x16x32_bf16 v[46:49], v[232:235], v[146:149], v[46:49]
	v_mfma_f32_16x16x32_bf16 v[14:17], v[236:239], v[146:149], v[14:17]
	s_waitcnt lgkmcnt(4)
	v_mfma_f32_16x16x32_bf16 v[42:45], v[232:235], v[150:153], v[42:45]
	v_mfma_f32_16x16x32_bf16 v[10:13], v[236:239], v[150:153], v[10:13]
	s_waitcnt lgkmcnt(2)
	v_mfma_f32_16x16x32_bf16 v[38:41], v[232:235], v[182:185], v[38:41]
	v_mfma_f32_16x16x32_bf16 v[6:9], v[236:239], v[182:185], v[6:9]
	s_waitcnt lgkmcnt(0)
	v_mfma_f32_16x16x32_bf16 v[34:37], v[232:235], v[240:243], v[34:37]
	v_mfma_f32_16x16x32_bf16 v[2:5], v[236:239], v[240:243], v[2:5]
	s_waitcnt vmcnt(0)
	s_andn2_b64 vcc, exec, s[12:13]
	s_waitcnt vmcnt(0) lgkmcnt(0)
	s_barrier
	s_cbranch_vccnz .LBB0_699
	ds_write_b128 v217, v[66:69]
	ds_write_b128 v218, v[70:73]
	ds_write_b128 v220, v[74:77]
	ds_write_b128 v221, v[78:81]
	s_branch .LBB0_699
